# attention P.V: transposed V fragment reads kept several deep in a growing ring of dead P-operand registers
# speedup vs baseline: 1.0025x; 1.0025x over previous
; #define LAS __attribute__((address_space(3)))
; __device__ __forceinline__ unsigned pk2(float lo, float hi) { f32x2_t v = {lo, hi}; bf16x2_t b = __builtin_convertvector(v, bf16x2_t); return __builtin_bit_cast(unsigned, b); }
; #define LBAR() do { asm volatile("s_waitcnt lgkmcnt(0)" ::: "memory"); __builtin_amdgcn_s_barrier(); asm volatile("" ::: "memory"); } while (0)
; __device__ __forceinline__ s16x4 vtr(const LAS unsigned char* p) { return __builtin_bit_cast(s16x4, __builtin_amdgcn_ds_read_tr16_b64_v4i16((LAS v4i16_t*)p)); }
; __device__ __forceinline__ void attn_phase(LAS unsigned char* lds, const bf16* __restrict__ Q, const bf16* __restrict__ Kb, const bf16* __restrict__ Vb, unsigned char* ws, float* PM, int tid, int wave, int lane) {
;     ...
;             for (int s2 = 0; s2 < 2; ++s2) { pw[i][s2].x = pk2(sacc[i][8 * s2], sacc[i][8 * s2 + 1]); pw[i][s2].y = pk2(sacc[i][8 * s2 + 2], sacc[i][8 * s2 + 3]); pw[i][s2].z = pk2(sacc[i][8 * s2 + 4], sacc[i][8 * s2 + 5]); pw[i][s2].w = pk2(sacc[i][8 * s2 + 6], sacc[i][8 * s2 + 7]); }
;         }
;         { auto rr = __builtin_amdgcn_permlane32_swap(__float_as_uint(l), __float_as_uint(l), false, false); l = __uint_as_float(rr[0]) + __uint_as_float(rr[1]); }
;         LBAR();
;         ATT_STAGE_WRITE(VROW);
;         LBAR();
;         const AttnItem C = I;
;         const int nxt = it + (int)gridDim.x; const bool more = nxt < 1536;
;         if (more) { I = attn_decode(nxt); ATT_STAGE_LOAD(Kb, I); ATT_QLOAD(I); }
;         f32x16 oacc[4];
; #pragma unroll
;         for (int i = 0; i < 4; ++i)
; #pragma unroll
;             for (int e = 0; e < 16; ++e) oacc[i][e] = 0.f;
;         const LAS unsigned char* vbase = lds + (32 * wave + 4 * h + ((lane & 15) >> 2)) * VROW + (16 * ((lane >> 4) & 1) + 4 * (lane & 3)) * 2;
; #pragma unroll
;         for (int i = 0; i < 5; ++i)
; #pragma unroll
;             for (int s2 = 0; s2 < 2; ++s2)
; #pragma unroll
;                 for (int db = 0; db < 4; ++db) {
;                     const s16x4 lo = vtr(vbase + (32 * i + 16 * s2) * VROW + db * 64), hi = vtr(vbase + (32 * i + 16 * s2 + 8) * VROW + db * 64);
;                     const bf16x8 av = {lo[0], lo[1], lo[2], lo[3], hi[0], hi[1], hi[2], hi[3]};
;                     oacc[db] = __builtin_amdgcn_mfma_f32_32x32x16_bf16(av, __builtin_bit_cast(bf16x8, pw[i][s2]), oacc[db], 0, 0, 0);
;                 }
.LBB0_594:
	v_cvt_pk_bf16_f32 v0, v4, v5
	v_cvt_pk_bf16_f32 v1, v6, v7
	ds_read_b64_tr_b16 v[4:5], v211
	ds_read_b64_tr_b16 v[6:7], v211 offset:2560
	v_cvt_pk_bf16_f32 v2, v8, v9
	v_cvt_pk_bf16_f32 v3, v10, v11
	v_cvt_pk_bf16_f32 v166, v48, v49
	v_cvt_pk_bf16_f32 v167, v50, v51
	v_cvt_pk_bf16_f32 v76, v52, v53
	v_cvt_pk_bf16_f32 v77, v54, v55
	v_cvt_pk_bf16_f32 v78, v56, v57
	v_cvt_pk_bf16_f32 v79, v58, v59
	v_cvt_pk_bf16_f32 v72, v60, v61
	v_cvt_pk_bf16_f32 v73, v62, v63
	s_waitcnt lgkmcnt(0)
	v_mfma_f32_32x32x16_bf16 v[48:63], v[4:7], v[0:3], 0
	ds_read_b64_tr_b16 v[4:5], v211 offset:64
	ds_read_b64_tr_b16 v[6:7], v211 offset:2624
	v_cvt_pk_bf16_f32 v174, v32, v33
	v_cvt_pk_bf16_f32 v175, v34, v35
	v_cvt_pk_bf16_f32 v168, v36, v37
	v_cvt_pk_bf16_f32 v169, v38, v39
	v_cvt_pk_bf16_f32 v170, v40, v41
	v_cvt_pk_bf16_f32 v171, v42, v43
	v_cvt_pk_bf16_f32 v164, v44, v45
	v_cvt_pk_bf16_f32 v165, v46, v47
	s_waitcnt lgkmcnt(0)
	v_mfma_f32_32x32x16_bf16 v[32:47], v[4:7], v[0:3], 0
	ds_read_b64_tr_b16 v[4:5], v211 offset:128
	ds_read_b64_tr_b16 v[6:7], v211 offset:2688
	v_cvt_pk_bf16_f32 v182, v16, v17
	v_cvt_pk_bf16_f32 v183, v18, v19
	v_cvt_pk_bf16_f32 v176, v20, v21
	v_cvt_pk_bf16_f32 v177, v22, v23
	v_cvt_pk_bf16_f32 v178, v24, v25
	v_cvt_pk_bf16_f32 v179, v26, v27
	v_cvt_pk_bf16_f32 v172, v28, v29
	v_cvt_pk_bf16_f32 v173, v30, v31
	v_cvt_pk_bf16_f32 v74, v64, v65
	v_cvt_pk_bf16_f32 v68, v68, v69
	v_cvt_pk_bf16_f32 v69, v70, v71
	v_cvt_pk_bf16_f32 v70, v197, v232
	v_cvt_pk_bf16_f32 v71, v233, v234
	v_cvt_pk_bf16_f32 v64, v235, v236
	s_waitcnt lgkmcnt(0)
	v_mfma_f32_32x32x16_bf16 v[16:31], v[4:7], v[0:3], 0
	ds_read_b64_tr_b16 v[4:5], v211 offset:192
	ds_read_b64_tr_b16 v[6:7], v211 offset:2752
	ds_read_b64_tr_b16 v[232:233], v211 offset:5120
	ds_read_b64_tr_b16 v[234:235], v211 offset:7680
	v_cvt_pk_bf16_f32 v180, v12, v13
	v_cvt_pk_bf16_f32 v181, v14, v15
	v_cvt_pk_bf16_f32 v75, v66, v67
	v_cvt_pk_bf16_f32 v65, v237, v238
	v_cvt_pk_bf16_f32 v66, v239, v240
	s_waitcnt lgkmcnt(0)
	v_mfma_f32_32x32x16_bf16 v[48:63], v[232:235], v[180:183], v[48:63]
	ds_read_b64_tr_b16 v[232:233], v211 offset:5184
	ds_read_b64_tr_b16 v[234:235], v211 offset:7744
	v_cvt_pk_bf16_f32 v67, v241, v242
	v_add_f32_e32 v197, v243, v244
	s_lshl_b32 s0, s93, 7
	s_waitcnt lgkmcnt(0)
	v_mfma_f32_32x32x16_bf16 v[32:47], v[232:235], v[180:183], v[32:47]
	ds_read_b64_tr_b16 v[232:233], v211 offset:5248
	ds_read_b64_tr_b16 v[234:235], v211 offset:7808
	v_mfma_f32_32x32x16_bf16 v[0:15], v[4:7], v[0:3], 0
	s_waitcnt lgkmcnt(0)
	v_mfma_f32_32x32x16_bf16 v[16:31], v[232:235], v[180:183], v[16:31]
	ds_read_b64_tr_b16 v[232:233], v211 offset:5312
	ds_read_b64_tr_b16 v[234:235], v211 offset:7872
	s_waitcnt lgkmcnt(0)
	v_mfma_f32_32x32x16_bf16 v[0:15], v[232:235], v[180:183], v[0:15]
	ds_read_b64_tr_b16 v[180:181], v211 offset:10240
	ds_read_b64_tr_b16 v[182:183], v211 offset:12800
	ds_read_b64_tr_b16 v[232:233], v211 offset:10304
	ds_read_b64_tr_b16 v[234:235], v211 offset:12864
	s_waitcnt lgkmcnt(2)
	v_mfma_f32_32x32x16_bf16 v[48:63], v[180:183], v[176:179], v[48:63]
	ds_read_b64_tr_b16 v[180:181], v211 offset:10368
	ds_read_b64_tr_b16 v[182:183], v211 offset:12928
	s_waitcnt lgkmcnt(2)
	v_mfma_f32_32x32x16_bf16 v[32:47], v[232:235], v[176:179], v[32:47]
	ds_read_b64_tr_b16 v[232:233], v211 offset:10432
	ds_read_b64_tr_b16 v[234:235], v211 offset:12992
	s_waitcnt lgkmcnt(2)
	v_mfma_f32_32x32x16_bf16 v[16:31], v[180:183], v[176:179], v[16:31]
	ds_read_b64_tr_b16 v[180:181], v211 offset:15360
	ds_read_b64_tr_b16 v[182:183], v211 offset:17920
	s_waitcnt lgkmcnt(2)
	v_mfma_f32_32x32x16_bf16 v[0:15], v[232:235], v[176:179], v[0:15]
	ds_read_b64_tr_b16 v[232:233], v211 offset:15424
	ds_read_b64_tr_b16 v[234:235], v211 offset:17984
	ds_read_b64_tr_b16 v[176:177], v211 offset:15488
	ds_read_b64_tr_b16 v[178:179], v211 offset:18048
	s_waitcnt lgkmcnt(4)
	v_mfma_f32_32x32x16_bf16 v[48:63], v[180:183], v[172:175], v[48:63]
	ds_read_b64_tr_b16 v[180:181], v211 offset:15552
	ds_read_b64_tr_b16 v[182:183], v211 offset:18112
	s_waitcnt lgkmcnt(4)
	v_mfma_f32_32x32x16_bf16 v[32:47], v[232:235], v[172:175], v[32:47]
	ds_read_b64_tr_b16 v[232:233], v211 offset:20480
	ds_read_b64_tr_b16 v[234:235], v211 offset:23040
	s_waitcnt lgkmcnt(4)
	v_mfma_f32_32x32x16_bf16 v[16:31], v[176:179], v[172:175], v[16:31]
	ds_read_b64_tr_b16 v[176:177], v211 offset:20544
	ds_read_b64_tr_b16 v[178:179], v211 offset:23104
	s_waitcnt lgkmcnt(4)
	v_mfma_f32_32x32x16_bf16 v[0:15], v[180:183], v[172:175], v[0:15]
	ds_read_b64_tr_b16 v[180:181], v211 offset:20608
	ds_read_b64_tr_b16 v[182:183], v211 offset:23168
	ds_read_b64_tr_b16 v[172:173], v211 offset:20672
	ds_read_b64_tr_b16 v[174:175], v211 offset:23232
	s_waitcnt lgkmcnt(6)
	v_mfma_f32_32x32x16_bf16 v[48:63], v[232:235], v[168:171], v[48:63]
	ds_read_b64_tr_b16 v[232:233], v211 offset:25600
	ds_read_b64_tr_b16 v[234:235], v211 offset:28160
	s_waitcnt lgkmcnt(6)
	v_mfma_f32_32x32x16_bf16 v[32:47], v[176:179], v[168:171], v[32:47]
	ds_read_b64_tr_b16 v[176:177], v211 offset:25664
	ds_read_b64_tr_b16 v[178:179], v211 offset:28224
	s_waitcnt lgkmcnt(6)
	v_mfma_f32_32x32x16_bf16 v[16:31], v[180:183], v[168:171], v[16:31]
	ds_read_b64_tr_b16 v[180:181], v211 offset:25728
	ds_read_b64_tr_b16 v[182:183], v211 offset:28288
	s_waitcnt lgkmcnt(6)
	v_mfma_f32_32x32x16_bf16 v[0:15], v[172:175], v[168:171], v[0:15]
	ds_read_b64_tr_b16 v[172:173], v211 offset:25792
	ds_read_b64_tr_b16 v[174:175], v211 offset:28352
	ds_read_b64_tr_b16 v[168:169], v211 offset:30720
	ds_read_b64_tr_b16 v[170:171], v211 offset:33280
	s_waitcnt lgkmcnt(8)
; #define LAS __attribute__((address_space(3)))
; __device__ __forceinline__ s16x4 vtr(const LAS unsigned char* p) { return __builtin_bit_cast(s16x4, __builtin_amdgcn_ds_read_tr16_b64_v4i16((LAS v4i16_t*)p)); }
; __device__ __forceinline__ void attn_phase(LAS unsigned char* lds, const bf16* __restrict__ Q, const bf16* __restrict__ Kb, const bf16* __restrict__ Vb, unsigned char* ws, float* PM, int tid, int wave, int lane) {
;     ...
;         const LAS unsigned char* vbase = lds + (32 * wave + 4 * h + ((lane & 15) >> 2)) * VROW + (16 * ((lane >> 4) & 1) + 4 * (lane & 3)) * 2;
; #pragma unroll
;         for (int i = 0; i < 5; ++i)
; #pragma unroll
;             for (int s2 = 0; s2 < 2; ++s2)
; #pragma unroll
;                 for (int db = 0; db < 4; ++db) {
;                     const s16x4 lo = vtr(vbase + (32 * i + 16 * s2) * VROW + db * 64), hi = vtr(vbase + (32 * i + 16 * s2 + 8) * VROW + db * 64);
;                     const bf16x8 av = {lo[0], lo[1], lo[2], lo[3], hi[0], hi[1], hi[2], hi[3]};
;                     oacc[db] = __builtin_amdgcn_mfma_f32_32x32x16_bf16(av, __builtin_bit_cast(bf16x8, pw[i][s2]), oacc[db], 0, 0, 0);
;                 }
	v_mfma_f32_32x32x16_bf16 v[48:63], v[232:235], v[164:167], v[48:63]
	ds_read_b64_tr_b16 v[232:233], v211 offset:30784
	ds_read_b64_tr_b16 v[234:235], v211 offset:33344
	s_waitcnt lgkmcnt(8)
	v_mfma_f32_32x32x16_bf16 v[32:47], v[176:179], v[164:167], v[32:47]
	ds_read_b64_tr_b16 v[176:177], v211 offset:30848
	ds_read_b64_tr_b16 v[178:179], v211 offset:33408
	s_waitcnt lgkmcnt(8)
	v_mfma_f32_32x32x16_bf16 v[16:31], v[180:183], v[164:167], v[16:31]
	ds_read_b64_tr_b16 v[180:181], v211 offset:30912
	ds_read_b64_tr_b16 v[182:183], v211 offset:33472
	s_waitcnt lgkmcnt(8)
	v_mfma_f32_32x32x16_bf16 v[0:15], v[172:175], v[164:167], v[0:15]
	ds_read_b64_tr_b16 v[172:173], v211 offset:35840
	ds_read_b64_tr_b16 v[174:175], v211 offset:38400
	ds_read_b64_tr_b16 v[164:165], v211 offset:35904
	ds_read_b64_tr_b16 v[166:167], v211 offset:38464
	s_waitcnt lgkmcnt(10)
	v_mfma_f32_32x32x16_bf16 v[48:63], v[168:171], v[76:79], v[48:63]
	ds_read_b64_tr_b16 v[168:169], v211 offset:35968
	ds_read_b64_tr_b16 v[170:171], v211 offset:38528
	s_waitcnt lgkmcnt(10)
	v_mfma_f32_32x32x16_bf16 v[32:47], v[232:235], v[76:79], v[32:47]
	ds_read_b64_tr_b16 v[232:233], v211 offset:36032
	ds_read_b64_tr_b16 v[234:235], v211 offset:38592
	s_waitcnt lgkmcnt(10)
	v_mfma_f32_32x32x16_bf16 v[16:31], v[176:179], v[76:79], v[16:31]
	ds_read_b64_tr_b16 v[176:177], v211 offset:40960
	ds_read_b64_tr_b16 v[178:179], v211 offset:43520
	s_waitcnt lgkmcnt(10)
	v_mfma_f32_32x32x16_bf16 v[0:15], v[180:183], v[76:79], v[0:15]
	ds_read_b64_tr_b16 v[180:181], v211 offset:41024
	ds_read_b64_tr_b16 v[182:183], v211 offset:43584
	s_waitcnt lgkmcnt(10)
	v_mfma_f32_32x32x16_bf16 v[48:63], v[172:175], v[72:75], v[48:63]
	ds_read_b64_tr_b16 v[76:77], v211 offset:41088
	ds_read_b64_tr_b16 v[78:79], v211 offset:43648
	s_waitcnt lgkmcnt(10)
	v_mfma_f32_32x32x16_bf16 v[32:47], v[164:167], v[72:75], v[32:47]
	ds_read_b64_tr_b16 v[172:173], v211 offset:41152
	ds_read_b64_tr_b16 v[174:175], v211 offset:43712
	s_waitcnt lgkmcnt(10)
	v_mfma_f32_32x32x16_bf16 v[16:31], v[168:171], v[72:75], v[16:31]
	ds_read_b64_tr_b16 v[164:165], v211 offset:46080
	ds_read_b64_tr_b16 v[166:167], v211 offset:48640
	s_waitcnt lgkmcnt(10)
	v_mfma_f32_32x32x16_bf16 v[0:15], v[232:235], v[72:75], v[0:15]
	ds_read_b64_tr_b16 v[168:169], v211 offset:46144
	ds_read_b64_tr_b16 v[170:171], v211 offset:48704
	s_waitcnt lgkmcnt(10)
	v_mfma_f32_32x32x16_bf16 v[48:63], v[176:179], v[68:71], v[48:63]
	ds_read_b64_tr_b16 v[232:233], v211 offset:46208
	ds_read_b64_tr_b16 v[234:235], v211 offset:48768
	s_waitcnt lgkmcnt(10)
	v_mfma_f32_32x32x16_bf16 v[32:47], v[180:183], v[68:71], v[32:47]
	ds_read_b64_tr_b16 v[72:73], v211 offset:46272
	ds_read_b64_tr_b16 v[74:75], v211 offset:48832
	s_waitcnt lgkmcnt(10)
	v_mfma_f32_32x32x16_bf16 v[16:31], v[76:79], v[68:71], v[16:31]
	s_waitcnt lgkmcnt(8)
	v_mfma_f32_32x32x16_bf16 v[0:15], v[172:175], v[68:71], v[0:15]
	s_waitcnt lgkmcnt(6)
	v_mfma_f32_32x32x16_bf16 v[48:63], v[164:167], v[64:67], v[48:63]
	s_waitcnt lgkmcnt(4)
	v_mfma_f32_32x32x16_bf16 v[32:47], v[168:171], v[64:67], v[32:47]
	s_waitcnt lgkmcnt(2)
	v_mfma_f32_32x32x16_bf16 v[16:31], v[232:235], v[64:67], v[16:31]
	s_waitcnt lgkmcnt(0)
; __device__ __forceinline__ unsigned pk2(float lo, float hi) { f32x2_t v = {lo, hi}; bf16x2_t b = __builtin_convertvector(v, bf16x2_t); return __builtin_bit_cast(unsigned, b); }
; __device__ __forceinline__ void attn_phase(LAS unsigned char* lds, const bf16* __restrict__ Q, const bf16* __restrict__ Kb, const bf16* __restrict__ Vb, unsigned char* ws, float* PM, int tid, int wave, int lane) {
;     ...
;         const float inv = 1.f / l;
;         const size_t qpos = (size_t)(C.lq0 + 32 * wave + r) * C.d + C.res;
;     ...
; #pragma unroll
;         for (int db = 0; db < 4; ++db)
; #pragma unroll
;             for (int ep = 0; ep < 2; ++ep) {
;                 const int e0 = 2 * ep, e1 = 2 * ep + 1;
;                 unsigned ax = pk2(oacc[db][4 * e0] * inv, oacc[db][4 * e0 + 1] * inv), ay = pk2(oacc[db][4 * e0 + 2] * inv, oacc[db][4 * e0 + 3] * inv);
;                 unsigned bx = pk2(oacc[db][4 * e1] * inv, oacc[db][4 * e1 + 1] * inv), by = pk2(oacc[db][4 * e1 + 2] * inv, oacc[db][4 * e1 + 3] * inv);
;                 { auto rx = __builtin_amdgcn_permlane32_swap(ax, bx, false, false); ax = rx[0]; bx = rx[1]; }
;                 { auto ry = __builtin_amdgcn_permlane32_swap(ay, by, false, false); ay = ry[0]; by = ry[1]; }
;                 u32x4 o = {ax, ay, bx, by};
;                 *(u32x4*)(po + 16 * (4 * db + e0)) = o;
;             }
;     ...
;         if (!more) break;
;         it = nxt;
	v_mfma_f32_32x32x16_bf16 v[0:15], v[72:75], v[64:67], v[0:15]
	v_div_scale_f32 v64, s[8:9], v197, v197, 1.0
	v_rcp_f32_e32 v65, v64
	s_nop 0
	v_fma_f32 v66, -v64, v65, 1.0
	v_fmac_f32_e32 v65, v66, v65
	v_div_scale_f32 v66, vcc, 1.0, v197, 1.0
	v_mul_f32_e32 v67, v66, v65
	v_fma_f32 v68, -v64, v67, v66
	v_fmac_f32_e32 v67, v68, v65
	v_fma_f32 v64, -v64, v67, v66
	v_div_fmas_f32 v64, v64, v65, v67
	v_div_fixup_f32 v66, v64, v197, 1.0
	v_add_u32_e32 v67, s85, v210
	v_mov_b64_e32 v[64:65], s[96:97]
	v_mad_u64_u32 v[64:65], s[8:9], v67, s3, v[64:65]
	v_ashrrev_i32_e32 v69, 31, v67
	v_mov_b32_e32 v68, v65
	v_mad_u64_u32 v[68:69], s[8:9], v69, s3, v[68:69]
	s_ashr_i32 s85, s84, 31
	s_lshl_b64 s[8:9], s[84:85], 25
	s_add_u32 s1, s8, 0x1b400000
	s_addc_u32 s3, s9, 0
	s_cmp_lt_i32 s84, 2
	s_cselect_b32 s1, s1, 0x12c00000
	v_mov_b32_e32 v65, v68
	s_cselect_b32 s3, s3, 0
	s_add_u32 s8, s88, s1
	s_addc_u32 s9, s89, s3
	s_cmp_lt_i32 s84, 2
	v_readlane_b32 s1, v245, 15
	v_readlane_b32 s3, v245, 16
	s_cselect_b32 s8, s8, s1
	s_cselect_b32 s9, s9, s3
	v_lshlrev_b64 v[68:69], 11, v[64:65]
	v_pk_mul_f32 v[48:49], v[66:67], v[48:49] op_sel_hi:[0,1]
	v_pk_mul_f32 v[50:51], v[66:67], v[50:51] op_sel_hi:[0,1]
	v_pk_mul_f32 v[32:33], v[66:67], v[32:33] op_sel_hi:[0,1]
	v_pk_mul_f32 v[34:35], v[66:67], v[34:35] op_sel_hi:[0,1]
	v_pk_mul_f32 v[16:17], v[66:67], v[16:17] op_sel_hi:[0,1]
	v_pk_mul_f32 v[18:19], v[66:67], v[18:19] op_sel_hi:[0,1]
	v_pk_mul_f32 v[0:1], v[66:67], v[0:1] op_sel_hi:[0,1]
	v_pk_mul_f32 v[2:3], v[66:67], v[2:3] op_sel_hi:[0,1]
	v_lshl_add_u64 v[68:69], s[8:9], 0, v[68:69]
	s_lshl_b32 s96, s0, 1
	v_cvt_pk_bf16_f32 v48, v48, v49
	v_cvt_pk_bf16_f32 v49, v50, v51
	v_pk_mul_f32 v[50:51], v[66:67], v[52:53] op_sel_hi:[0,1]
	v_pk_mul_f32 v[52:53], v[66:67], v[54:55] op_sel_hi:[0,1]
	v_cvt_pk_bf16_f32 v32, v32, v33
	v_cvt_pk_bf16_f32 v33, v34, v35
	v_pk_mul_f32 v[34:35], v[66:67], v[36:37] op_sel_hi:[0,1]
	v_pk_mul_f32 v[36:37], v[66:67], v[38:39] op_sel_hi:[0,1]
	v_cvt_pk_bf16_f32 v16, v16, v17
	v_cvt_pk_bf16_f32 v17, v18, v19
	v_pk_mul_f32 v[18:19], v[66:67], v[20:21] op_sel_hi:[0,1]
	v_pk_mul_f32 v[20:21], v[66:67], v[22:23] op_sel_hi:[0,1]
	v_cvt_pk_bf16_f32 v0, v0, v1
	v_cvt_pk_bf16_f32 v1, v2, v3
	v_pk_mul_f32 v[2:3], v[66:67], v[4:5] op_sel_hi:[0,1]
	v_pk_mul_f32 v[4:5], v[66:67], v[6:7] op_sel_hi:[0,1]
	v_lshl_add_u64 v[68:69], v[68:69], 0, s[96:97]
	v_cvt_pk_bf16_f32 v50, v50, v51
	v_cvt_pk_bf16_f32 v51, v52, v53
	v_cvt_pk_bf16_f32 v34, v34, v35
	v_cvt_pk_bf16_f32 v35, v36, v37
	v_cvt_pk_bf16_f32 v18, v18, v19
	v_cvt_pk_bf16_f32 v19, v20, v21
	v_cvt_pk_bf16_f32 v2, v2, v3
	v_cvt_pk_bf16_f32 v3, v4, v5
	v_lshl_add_u64 v[68:69], v[68:69], 0, v[192:193]
	v_permlane32_swap_b32_e32 v48, v50
	v_permlane32_swap_b32_e32 v49, v51
	v_permlane32_swap_b32_e32 v32, v34
	v_permlane32_swap_b32_e32 v33, v35
	v_permlane32_swap_b32_e32 v16, v18
	v_permlane32_swap_b32_e32 v17, v19
	v_permlane32_swap_b32_e32 v0, v2
	v_permlane32_swap_b32_e32 v1, v3
	global_store_dwordx4 v[68:69], v[48:51], off
	global_store_dwordx4 v[68:69], v[32:35], off offset:64
	global_store_dwordx4 v[68:69], v[16:19], off offset:128
	v_pk_mul_f32 v[48:49], v[66:67], v[56:57] op_sel_hi:[0,1]
	v_pk_mul_f32 v[50:51], v[66:67], v[58:59] op_sel_hi:[0,1]
	v_pk_mul_f32 v[32:33], v[66:67], v[40:41] op_sel_hi:[0,1]
	v_pk_mul_f32 v[34:35], v[66:67], v[42:43] op_sel_hi:[0,1]
	v_pk_mul_f32 v[16:17], v[66:67], v[24:25] op_sel_hi:[0,1]
	v_pk_mul_f32 v[18:19], v[66:67], v[26:27] op_sel_hi:[0,1]
	global_store_dwordx4 v[68:69], v[0:3], off offset:192
	v_cvt_pk_bf16_f32 v48, v48, v49
	v_cvt_pk_bf16_f32 v49, v50, v51
	v_pk_mul_f32 v[0:1], v[66:67], v[8:9] op_sel_hi:[0,1]
	v_pk_mul_f32 v[2:3], v[66:67], v[10:11] op_sel_hi:[0,1]
	v_pk_mul_f32 v[50:51], v[66:67], v[60:61] op_sel_hi:[0,1]
	v_pk_mul_f32 v[52:53], v[66:67], v[62:63] op_sel_hi:[0,1]
	v_cvt_pk_bf16_f32 v32, v32, v33
	v_cvt_pk_bf16_f32 v33, v34, v35
	v_pk_mul_f32 v[34:35], v[66:67], v[44:45] op_sel_hi:[0,1]
	v_pk_mul_f32 v[36:37], v[66:67], v[46:47] op_sel_hi:[0,1]
	v_cvt_pk_bf16_f32 v16, v16, v17
	v_cvt_pk_bf16_f32 v17, v18, v19
	v_pk_mul_f32 v[18:19], v[66:67], v[28:29] op_sel_hi:[0,1]
	v_pk_mul_f32 v[20:21], v[66:67], v[30:31] op_sel_hi:[0,1]
	v_cvt_pk_bf16_f32 v0, v0, v1
	v_cvt_pk_bf16_f32 v1, v2, v3
	v_pk_mul_f32 v[2:3], v[66:67], v[12:13] op_sel_hi:[0,1]
	v_pk_mul_f32 v[4:5], v[66:67], v[14:15] op_sel_hi:[0,1]
	v_cvt_pk_bf16_f32 v50, v50, v51
	v_cvt_pk_bf16_f32 v51, v52, v53
	v_cvt_pk_bf16_f32 v34, v34, v35
	v_cvt_pk_bf16_f32 v35, v36, v37
	v_cvt_pk_bf16_f32 v18, v18, v19
	v_cvt_pk_bf16_f32 v19, v20, v21
	v_cvt_pk_bf16_f32 v2, v2, v3
	v_cvt_pk_bf16_f32 v3, v4, v5
	v_permlane32_swap_b32_e32 v48, v50
	v_permlane32_swap_b32_e32 v49, v51
	v_permlane32_swap_b32_e32 v32, v34
	v_permlane32_swap_b32_e32 v33, v35
	v_permlane32_swap_b32_e32 v16, v18
	v_permlane32_swap_b32_e32 v17, v19
	v_permlane32_swap_b32_e32 v0, v2
	v_permlane32_swap_b32_e32 v1, v3
	global_store_dwordx4 v[68:69], v[48:51], off offset:32
	global_store_dwordx4 v[68:69], v[32:35], off offset:96
	global_store_dwordx4 v[68:69], v[16:19], off offset:160
	global_store_dwordx4 v[68:69], v[0:3], off offset:224
	s_mov_b64 s[0:1], exec
	v_readlane_b32 s8, v245, 46
	v_readlane_b32 s9, v245, 47
	s_and_b64 s[8:9], s[0:1], s[8:9]
	s_mov_b64 exec, s[8:9]
	s_cbranch_execz .LBB0_573
	s_lshl_b64 s[8:9], s[84:85], 17
	v_lshl_add_u64 v[0:1], v[64:65], 3, s[8:9]
	v_readlane_b32 s8, v245, 38
	v_or_b32_e32 v0, s93, v0
	v_readlane_b32 s9, v245, 39
	s_nop 1
	v_lshl_add_u64 v[0:1], v[0:1], 3, s[8:9]
	global_store_dwordx2 v[0:1], v[196:197], off
	s_branch .LBB0_573
